# attention fast path: softmax VALU interleaved into P.V MFMAs, K/V LDS-DMA issue and P-fragment selects interleaved into the QK^T chain; mLSTM stage C/A staging loads batched, parallel prefix max, outp
# speedup vs baseline: 1.0177x; 1.0119x over previous
.Li0_entry:
	v_add_u32_e32 v167, s79, v147
	v_add_u32_e32 v188, s79, v149
	v_add_u32_e32 v189, s79, v151
	v_add_u32_e32 v190, s79, v153
	ds_read_b128 v[64:67], v167
	ds_read_b128 v[180:183], v188
	s_waitcnt lgkmcnt(2)
	v_max_f32_e32 v72, v166, v166
	v_max_f32_e32 v73, v164, v164
	v_max_f32_e32 v72, v73, v72
	v_sub_f32_e32 v73, v72, v165
	v_mul_f32_e32 v73, 0x3db504f3, v73
	v_cmp_ge_f32_e32 vcc, s88, v73
	s_cmp_eq_u64 vcc, exec
	s_cbranch_scc0 .Li0_orig
	s_waitcnt lgkmcnt(0)
	v_mfma_f32_32x32x16_bf16 v[64:79], v[64:67], v[80:83], 0
	v_mfma_f32_32x32x16_bf16 v[64:79], v[180:183], v[84:87], v[64:79]
	ds_read_b128 v[180:183], v189
	s_mov_b64 s[54:55], 0xe404000
	s_add_i32 m0, s96, 0x8000
	v_lshl_add_u64 v[184:185], v[134:135], 0, s[54:55]
	s_nop 0
	global_load_lds_dwordx4 v[184:185], off
	v_cndmask_b32_e64 v173, v113, v121, s[2:3]
	v_cndmask_b32_e64 v172, v112, v120, s[2:3]
	v_cndmask_b32_e64 v177, v121, v113, s[2:3]
	v_cndmask_b32_e64 v176, v120, v112, s[2:3]
	s_waitcnt lgkmcnt(0)
	v_mfma_f32_32x32x16_bf16 v[64:79], v[180:183], v[88:91], v[64:79]
	ds_read_b128 v[180:183], v190
	s_mov_b64 s[54:55], 0xe406000
	s_add_i32 m0, s96, 0xa000
	v_lshl_add_u64 v[184:185], v[134:135], 0, s[54:55]
	s_nop 0
	global_load_lds_dwordx4 v[184:185], off
	v_cndmask_b32_e64 v171, v119, v127, s[2:3]
	v_cndmask_b32_e64 v170, v118, v126, s[2:3]
	v_cndmask_b32_e64 v169, v117, v125, s[2:3]
	v_cndmask_b32_e64 v168, v116, v124, s[2:3]
	s_waitcnt lgkmcnt(0)
	v_mfma_f32_32x32x16_bf16 v[64:79], v[180:183], v[92:95], v[64:79]
	ds_read_b128 v[180:183], v167 offset:128
	s_mov_b64 s[54:55], 0xe804000
	s_add_i32 m0, s96, 0xc000
	v_lshl_add_u64 v[184:185], v[134:135], 0, s[54:55]
	s_nop 0
	global_load_lds_dwordx4 v[184:185], off
	v_cndmask_b32_e64 v175, v115, v123, s[2:3]
	v_cndmask_b32_e64 v174, v114, v122, s[2:3]
	v_cndmask_b32_e64 v127, v127, v119, s[2:3]
	v_cndmask_b32_e64 v126, v126, v118, s[2:3]
	s_waitcnt lgkmcnt(0)
	v_mfma_f32_32x32x16_bf16 v[64:79], v[180:183], v[96:99], v[64:79]
	ds_read_b128 v[180:183], v188 offset:128
	s_mov_b64 s[54:55], 0xe806000
	s_add_i32 m0, s96, 0xe000
	v_lshl_add_u64 v[184:185], v[134:135], 0, s[54:55]
	s_nop 0
	global_load_lds_dwordx4 v[184:185], off
	v_cndmask_b32_e64 v125, v125, v117, s[2:3]
	v_cndmask_b32_e64 v124, v124, v116, s[2:3]
	v_cndmask_b32_e64 v179, v123, v115, s[2:3]
	v_cndmask_b32_e64 v178, v122, v114, s[2:3]
	s_waitcnt lgkmcnt(0)
	v_mfma_f32_32x32x16_bf16 v[64:79], v[180:183], v[100:103], v[64:79]
	ds_read_b128 v[180:183], v189 offset:128
	s_cmp_gt_i32 s19, s18
	s_cbranch_scc1 .Li0_kskip
	v_lshl_add_u64 v[186:187], s[50:51], 0, v[130:131]
	s_mov_b64 s[54:55], 0xc408000
	s_mov_b32 m0, s97
	v_lshl_add_u64 v[184:185], v[186:187], 0, s[54:55]
	s_mov_b64 s[54:55], 0xc40a000
	global_load_lds_dwordx4 v[184:185], off
	s_mov_b32 m0, s26
	v_lshl_add_u64 v[186:187], v[186:187], 0, s[54:55]
	s_nop 0
	global_load_lds_dwordx4 v[186:187], off
.Li0_kskip:
	s_waitcnt lgkmcnt(0)
	v_mfma_f32_32x32x16_bf16 v[64:79], v[180:183], v[104:107], v[64:79]
	ds_read_b128 v[180:183], v190 offset:128
	v_mov_b32_e32 v166, v165
	s_waitcnt lgkmcnt(0)
	v_mfma_f32_32x32x16_bf16 v[64:79], v[180:183], v[108:111], v[64:79]
	s_sub_i32 s52, s83, 64
	s_cmp_le_i32 s52, s25
	s_cbranch_scc1 .Li0_sm
	s_nop 7
	v_add_u32_e32 v112, 0x5b, v162
	v_cmp_gt_u32_e32 vcc, s86, v112
	v_add_u32_e32 v112, s83, v163
	v_add_u32_e32 v112, 0xffffffa1, v112
	v_cndmask_b32_e32 v64, v141, v64, vcc
	v_cmp_lt_u32_e32 vcc, s87, v112
	v_add_u32_e32 v112, 0x59, v162
	s_nop 0
	v_cndmask_b32_e32 v65, v141, v65, vcc
	v_cmp_gt_u32_e32 vcc, s86, v112
	v_add_u32_e32 v112, 0x58, v162
	s_nop 0
	v_cndmask_b32_e32 v66, v141, v66, vcc
	v_cmp_gt_u32_e32 vcc, s86, v112
	v_add_u32_e32 v112, 0x53, v162
	s_nop 0
	v_cndmask_b32_e32 v67, v141, v67, vcc
	v_cmp_gt_u32_e32 vcc, s86, v112
	v_add_u32_e32 v112, 0x52, v162
	s_nop 0
	v_cndmask_b32_e32 v68, v141, v68, vcc
	v_cmp_gt_u32_e32 vcc, s86, v112
	v_add_u32_e32 v112, 0x51, v162
	s_nop 0
	v_cndmask_b32_e32 v69, v141, v69, vcc
	v_cmp_gt_u32_e32 vcc, s86, v112
	v_add_u32_e32 v112, 0x50, v162
	s_nop 0
	v_cndmask_b32_e32 v70, v141, v70, vcc
	v_cmp_gt_u32_e32 vcc, s86, v112
	v_add_u32_e32 v112, 0x4b, v162
	s_nop 0
	v_cndmask_b32_e32 v71, v141, v71, vcc
	v_cmp_gt_u32_e32 vcc, s86, v112
	v_add_u32_e32 v112, 0x4a, v162
	s_nop 0
	v_cndmask_b32_e32 v72, v141, v72, vcc
	v_cmp_gt_u32_e32 vcc, s86, v112
	v_add_u32_e32 v112, 0x49, v162
	s_nop 0
	v_cndmask_b32_e32 v73, v141, v73, vcc
	v_cmp_gt_u32_e32 vcc, s86, v112
	v_add_u32_e32 v112, 0x48, v162
	s_nop 0
	v_cndmask_b32_e32 v74, v141, v74, vcc
	v_cmp_gt_u32_e32 vcc, s86, v112
	v_add_u32_e32 v112, 0x43, v162
	s_nop 0
	v_cndmask_b32_e32 v75, v141, v75, vcc
	v_cmp_gt_u32_e32 vcc, s86, v112
	v_add_u32_e32 v112, 0x42, v162
	s_nop 0
	v_cndmask_b32_e32 v76, v141, v76, vcc
	v_cmp_gt_u32_e32 vcc, s86, v112
	v_add_u32_e32 v112, 0x41, v162
	s_nop 0
	v_cndmask_b32_e32 v77, v141, v77, vcc
	v_cmp_gt_u32_e32 vcc, s86, v112
	v_add_u32_e32 v112, 64, v162
	s_nop 0
	v_cndmask_b32_e32 v78, v141, v78, vcc
	v_cmp_gt_u32_e32 vcc, s86, v112
	s_nop 1
	v_cndmask_b32_e32 v79, v141, v79, vcc

.Li0_orig:
	s_waitcnt lgkmcnt(0)
	s_mov_b64 s[54:55], 0xe404000
	v_lshl_add_u64 v[64:65], v[134:135], 0, s[54:55]
	s_add_i32 m0, s96, 0x8000
	s_mov_b64 s[54:55], 0xe406000
	global_load_lds_dwordx4 v[64:65], off
	v_lshl_add_u64 v[64:65], v[134:135], 0, s[54:55]
	s_add_i32 m0, s96, 0xa000
	s_mov_b64 s[54:55], 0xe804000
	global_load_lds_dwordx4 v[64:65], off
	v_lshl_add_u64 v[64:65], v[134:135], 0, s[54:55]
	s_add_i32 m0, s96, 0xc000
	s_mov_b64 s[54:55], 0xe806000
	global_load_lds_dwordx4 v[64:65], off
	v_lshl_add_u64 v[64:65], v[134:135], 0, s[54:55]
	s_add_i32 m0, s96, 0xe000
	s_cmp_gt_i32 s19, s18
	global_load_lds_dwordx4 v[64:65], off
	s_cbranch_scc1 .LBB0_737
	v_lshl_add_u64 v[64:65], s[50:51], 0, v[130:131]
	s_mov_b64 s[54:55], 0xc40a000
	v_lshl_add_u64 v[66:67], v[64:65], 0, s[54:55]
	s_mov_b64 s[54:55], 0xc408000
	s_mov_b32 m0, s97
	v_lshl_add_u64 v[64:65], v[64:65], 0, s[54:55]
	global_load_lds_dwordx4 v[64:65], off
	s_mov_b32 m0, s26
	s_nop 0
	global_load_lds_dwordx4 v[66:67], off

.Li1_entry:
	ds_read_b128 v[64:67], v148
	ds_read_b128 v[180:183], v150
	s_waitcnt lgkmcnt(2)
	v_max_f32_e32 v72, v128, v128
	v_max_f32_e32 v73, v164, v164
	v_max_f32_e32 v72, v73, v72
	v_sub_f32_e32 v73, v72, v166
	v_mul_f32_e32 v73, 0x3db504f3, v73
	v_cmp_ge_f32_e32 vcc, s88, v73
	s_cmp_eq_u64 vcc, exec
	s_cbranch_scc0 .Li1_orig
	s_waitcnt lgkmcnt(0)
	v_mfma_f32_32x32x16_bf16 v[64:79], v[64:67], v[80:83], 0
	v_mfma_f32_32x32x16_bf16 v[64:79], v[180:183], v[84:87], v[64:79]
	ds_read_b128 v[180:183], v152
	s_mov_b64 s[56:57], 0xe408000
	s_mov_b32 m0, s96
	v_lshl_add_u64 v[184:185], v[134:135], 0, s[56:57]
	s_nop 0
	global_load_lds_dwordx4 v[184:185], off
	v_cndmask_b32_e64 v173, v113, v121, s[2:3]
	v_cndmask_b32_e64 v172, v112, v120, s[2:3]
	v_cndmask_b32_e64 v177, v121, v113, s[2:3]
	v_cndmask_b32_e64 v176, v120, v112, s[2:3]
	s_waitcnt lgkmcnt(0)
	v_mfma_f32_32x32x16_bf16 v[64:79], v[180:183], v[88:91], v[64:79]
	ds_read_b128 v[180:183], v154
	s_mov_b64 s[56:57], 0xe40a000
	s_mov_b32 m0, s6
	v_lshl_add_u64 v[184:185], v[134:135], 0, s[56:57]
	s_nop 0
	global_load_lds_dwordx4 v[184:185], off
	v_cndmask_b32_e64 v171, v127, v119, s[2:3]
	v_cndmask_b32_e64 v170, v126, v118, s[2:3]
	v_cndmask_b32_e64 v169, v125, v117, s[2:3]
	v_cndmask_b32_e64 v168, v124, v116, s[2:3]
	s_waitcnt lgkmcnt(0)
	v_mfma_f32_32x32x16_bf16 v[64:79], v[180:183], v[92:95], v[64:79]
	ds_read_b128 v[180:183], v148 offset:128
	s_mov_b64 s[56:57], 0xe808000
	s_mov_b32 m0, s7
	v_lshl_add_u64 v[184:185], v[134:135], 0, s[56:57]
	s_nop 0
	global_load_lds_dwordx4 v[184:185], off
	v_cndmask_b32_e64 v175, v115, v123, s[2:3]
	v_cndmask_b32_e64 v174, v114, v122, s[2:3]
	v_cndmask_b32_e64 v127, v119, v127, s[2:3]
	v_cndmask_b32_e64 v126, v118, v126, s[2:3]
	s_waitcnt lgkmcnt(0)
	v_mfma_f32_32x32x16_bf16 v[64:79], v[180:183], v[96:99], v[64:79]
	ds_read_b128 v[180:183], v150 offset:128
	s_mov_b64 s[56:57], 0xe80a000
	s_mov_b32 m0, s24
	v_lshl_add_u64 v[184:185], v[134:135], 0, s[56:57]
	s_nop 0
	global_load_lds_dwordx4 v[184:185], off
	v_cndmask_b32_e64 v125, v117, v125, s[2:3]
	v_cndmask_b32_e64 v124, v116, v124, s[2:3]
	v_cndmask_b32_e64 v179, v123, v115, s[2:3]
	v_cndmask_b32_e64 v178, v122, v114, s[2:3]
	s_waitcnt lgkmcnt(0)
	v_mfma_f32_32x32x16_bf16 v[64:79], v[180:183], v[100:103], v[64:79]
	ds_read_b128 v[180:183], v152 offset:128
	s_add_i32 s56, s19, 1
	s_cmp_gt_i32 s56, s18
	s_cbranch_scc1 .Li1_kskip
	v_lshl_add_u64 v[186:187], s[50:51], 0, v[130:131]
	s_mov_b64 s[56:57], 0xc40c000
	s_mov_b32 m0, s27
	v_lshl_add_u64 v[184:185], v[186:187], 0, s[56:57]
	s_mov_b64 s[56:57], 0xc40e000
	global_load_lds_dwordx4 v[184:185], off
	s_mov_b32 m0, s62
	v_lshl_add_u64 v[186:187], v[186:187], 0, s[56:57]
	s_nop 0
	global_load_lds_dwordx4 v[186:187], off
.Li1_kskip:
	s_waitcnt lgkmcnt(0)
	v_mfma_f32_32x32x16_bf16 v[64:79], v[180:183], v[104:107], v[64:79]
	ds_read_b128 v[180:183], v154 offset:128
	v_mov_b32_e32 v165, v166
	s_waitcnt lgkmcnt(0)
	v_mfma_f32_32x32x16_bf16 v[64:79], v[180:183], v[108:111], v[64:79]
	s_cmp_le_i32 s83, s25
	s_cbranch_scc1 .Li1_sm
	s_nop 7
	v_add_u32_e32 v112, 27, v162
	v_cmp_gt_u32_e32 vcc, s86, v112
	v_add_u32_e32 v112, s83, v163
	v_subrev_u32_e32 v112, 31, v112
	v_cndmask_b32_e32 v64, v141, v64, vcc
	v_cmp_lt_u32_e32 vcc, s87, v112
	v_add_u32_e32 v112, 25, v162
	s_nop 0
	v_cndmask_b32_e32 v65, v141, v65, vcc
	v_cmp_gt_u32_e32 vcc, s86, v112
	v_add_u32_e32 v112, 24, v162
	s_nop 0
	v_cndmask_b32_e32 v66, v141, v66, vcc
	v_cmp_gt_u32_e32 vcc, s86, v112
	v_add_u32_e32 v112, 19, v162
	s_nop 0
	v_cndmask_b32_e32 v67, v141, v67, vcc
	v_cmp_gt_u32_e32 vcc, s86, v112
	v_add_u32_e32 v112, 18, v162
	s_nop 0
	v_cndmask_b32_e32 v68, v141, v68, vcc
	v_cmp_gt_u32_e32 vcc, s86, v112
	v_add_u32_e32 v112, 17, v162
	s_nop 0
	v_cndmask_b32_e32 v69, v141, v69, vcc
	v_cmp_gt_u32_e32 vcc, s86, v112
	v_add_u32_e32 v112, 16, v162
	s_nop 0
	v_cndmask_b32_e32 v70, v141, v70, vcc
	v_cmp_gt_u32_e32 vcc, s86, v112
	v_add_u32_e32 v112, 11, v162
	s_nop 0
	v_cndmask_b32_e32 v71, v141, v71, vcc
	v_cmp_gt_u32_e32 vcc, s86, v112
	v_add_u32_e32 v112, 10, v162
	s_nop 0
	v_cndmask_b32_e32 v72, v141, v72, vcc
	v_cmp_gt_u32_e32 vcc, s86, v112
	v_add_u32_e32 v112, 9, v162
	s_nop 0
	v_cndmask_b32_e32 v73, v141, v73, vcc
	v_cmp_gt_u32_e32 vcc, s86, v112
	v_add_u32_e32 v112, 8, v162
	s_nop 0
	v_cndmask_b32_e32 v74, v141, v74, vcc
	v_cmp_gt_u32_e32 vcc, s86, v112
	v_add_u32_e32 v112, 3, v162
	s_nop 0
	v_cndmask_b32_e32 v75, v141, v75, vcc
	v_cmp_gt_u32_e32 vcc, s86, v112
	v_add_u32_e32 v112, 2, v162
	s_nop 0
	v_cndmask_b32_e32 v76, v141, v76, vcc
	v_cmp_gt_u32_e32 vcc, s86, v112
	v_add_u32_e32 v112, 1, v162
	s_nop 0
	v_cndmask_b32_e32 v77, v141, v77, vcc
	v_cmp_gt_u32_e32 vcc, s86, v112
	s_nop 1
	v_cndmask_b32_e32 v78, v141, v78, vcc
	v_cmp_gt_u32_e32 vcc, s86, v162
	s_nop 1
	v_cndmask_b32_e32 v79, v141, v79, vcc

.Li1_orig:
	s_waitcnt lgkmcnt(0)
	s_mov_b64 s[56:57], 0xe408000
	s_mov_b32 m0, s96
	v_lshl_add_u64 v[64:65], v[134:135], 0, s[56:57]
	s_mov_b64 s[56:57], 0xe40a000
	global_load_lds_dwordx4 v[64:65], off
	v_lshl_add_u64 v[64:65], v[134:135], 0, s[56:57]
	s_mov_b32 m0, s6
	s_mov_b64 s[56:57], 0xe808000
	global_load_lds_dwordx4 v[64:65], off
	v_lshl_add_u64 v[64:65], v[134:135], 0, s[56:57]
	s_mov_b32 m0, s7
	s_mov_b64 s[56:57], 0xe80a000
	global_load_lds_dwordx4 v[64:65], off
	v_lshl_add_u64 v[64:65], v[134:135], 0, s[56:57]
	s_mov_b32 m0, s24
	s_add_i32 s56, s19, 1
	global_load_lds_dwordx4 v[64:65], off
	s_cmp_gt_i32 s56, s18
	s_cbranch_scc1 .LBB0_751
	v_lshl_add_u64 v[64:65], s[50:51], 0, v[130:131]
	s_mov_b64 s[56:57], 0xc40e000
	v_lshl_add_u64 v[66:67], v[64:65], 0, s[56:57]
	s_mov_b64 s[56:57], 0xc40c000
	s_mov_b32 m0, s27
	v_lshl_add_u64 v[64:65], v[64:65], 0, s[56:57]
	global_load_lds_dwordx4 v[64:65], off
	s_mov_b32 m0, s62
	s_nop 0
	global_load_lds_dwordx4 v[66:67], off
